# s15 + attention: first 12 ops of the row-max chain run before the first P.V MFMA (while the V fragments are in flight); later softmax chunks two MFMA gaps earlier
# baseline (speedup 1.0000x reference)
; __device__ __forceinline__ void finishSM(f32x16& p0, f32x16& p1, float alpha, float& l_reg, bf16x8& pa0, bf16x8& pa1, bf16x8& pa2, bf16x8& pa3) {
;   for (int r = 0; r < 16; ++r) p1[r] = __builtin_amdgcn_exp2f(p1[r]);
;   float ps = 0; for (int r = 0; r < 16; ++r) ps += p0[r]; for (int r = 0; r < 16; ++r) ps += p1[r];
;   { auto rr = __builtin_amdgcn_permlane32_swap(__float_as_uint(ps), __float_as_uint(ps), false, false);
;     ps = __uint_as_float(rr[0]) + __uint_as_float(rr[1]); }
;   l_reg = l_reg * alpha + ps;
;     ...
;   PK4(p0, 0, pa0); PK4(p0, 8, pa1); PK4(p1, 0, pa2); PK4(p1, 8, pa3);
;     ...
; }
; __device__ __forceinline__ void qkt(f32x16& p0, f32x16& p1, const bf16* Ks, const bf16x8* qr, int r32, int hi) {
;   p0 = f32x16{}; p1 = f32x16{};
;   for (int d0 = 0; d0 < 8; ++d0) { int cb = (d0 * 16 + hi * 8) * 2;
;     bf16x8 b0 = *reinterpret_cast<const bf16x8*>((const char*)Ks + KSWZ(r32, cb));
;     bf16x8 b1 = *reinterpret_cast<const bf16x8*>((const char*)Ks + KSWZ(32 + r32, cb));
;     p0 = __builtin_amdgcn_mfma_f32_32x32x16_bf16(b0, qr[d0], p0, 0, 0, 0);
;     p1 = __builtin_amdgcn_mfma_f32_32x32x16_bf16(b1, qr[d0], p1, 0, 0, 0); }
.LBB0_602:
	ds_read_b128 v[64:67], v192 offset:49152
	ds_read_b128 v[68:71], v192 offset:57344
	ds_read_b128 v[242:245], v201 offset:49152
	ds_read_b128 v[246:249], v201 offset:57344
	v_exp_f32_e32 v160, v162
	v_add_f32_e32 v162, 0, v223
	s_waitcnt lgkmcnt(3)
	v_mfma_f32_32x32x16_bf16 v[80:95], v[64:67], v[126:129], 0
	v_add_f32_e32 v162, v224, v162
	v_add_f32_e32 v162, v225, v162
	v_add_f32_e32 v162, v227, v162
	v_add_f32_e32 v162, v229, v162
	v_add_f32_e32 v162, v230, v162
	v_add_f32_e32 v162, v226, v162
	v_add_f32_e32 v162, v228, v162
	s_waitcnt lgkmcnt(2)
	v_mfma_f32_32x32x16_bf16 v[64:79], v[68:71], v[126:129], 0
	v_add_f32_e32 v162, v215, v162
	v_add_f32_e32 v162, v217, v162
	v_add_f32_e32 v162, v219, v162
	v_add_f32_e32 v162, v221, v162
	v_add_f32_e32 v162, v216, v162
	v_add_f32_e32 v162, v218, v162
	v_add_f32_e32 v162, v220, v162
	s_waitcnt lgkmcnt(1)
	v_mfma_f32_32x32x16_bf16 v[80:95], v[242:245], v[122:125], v[80:95]
	v_add_f32_e32 v162, v222, v162
	v_exp_f32_e32 v154, v164
	v_exp_f32_e32 v155, v165
	v_exp_f32_e32 v156, v172
	v_exp_f32_e32 v157, v173
	v_exp_f32_e32 v158, v168
	v_exp_f32_e32 v159, v169
	s_waitcnt lgkmcnt(0)
	v_mfma_f32_32x32x16_bf16 v[64:79], v[246:249], v[122:125], v[64:79]
	ds_read_b128 v[242:245], v200 offset:49152
	ds_read_b128 v[246:249], v200 offset:57344
	v_exp_f32_e32 v161, v163
	v_cvt_pk_bf16_f32 v164, v229, v230
	v_cvt_pk_bf16_f32 v163, v225, v227
	v_cvt_pk_bf16_f32 v165, v226, v228
	v_cvt_pk_bf16_f32 v168, v216, v218
	v_cvt_pk_bf16_f32 v169, v220, v222
	s_waitcnt lgkmcnt(1)
	v_mfma_f32_32x32x16_bf16 v[80:95], v[242:245], v[134:137], v[80:95]
	v_exp_f32_e32 v146, v176
	v_exp_f32_e32 v147, v177
	v_exp_f32_e32 v148, v174
	v_exp_f32_e32 v149, v175
	v_permlane32_swap_b32_e32 v163, v165
	s_waitcnt lgkmcnt(0)
	v_mfma_f32_32x32x16_bf16 v[64:79], v[246:249], v[134:137], v[64:79]
	ds_read_b128 v[242:245], v195 offset:49152
	ds_read_b128 v[246:249], v195 offset:57344
	v_add_f32_e32 v162, v146, v162
	v_add_f32_e32 v162, v147, v162
	v_add_f32_e32 v162, v148, v162
	v_exp_f32_e32 v150, v170
	s_waitcnt lgkmcnt(1)
	v_mfma_f32_32x32x16_bf16 v[80:95], v[242:245], v[130:133], v[80:95]
	v_exp_f32_e32 v151, v171
	v_exp_f32_e32 v152, v166
	v_exp_f32_e32 v153, v167
	v_add_f32_e32 v162, v149, v162
	s_waitcnt lgkmcnt(0)
	v_mfma_f32_32x32x16_bf16 v[64:79], v[246:249], v[130:133], v[64:79]
	ds_read_b128 v[242:245], v194 offset:49152
	ds_read_b128 v[246:249], v194 offset:57344
	v_add_f32_e32 v162, v150, v162
	v_add_f32_e32 v162, v151, v162
	v_add_f32_e32 v162, v152, v162
	v_add_f32_e32 v162, v153, v162
	s_waitcnt lgkmcnt(1)
	v_mfma_f32_32x32x16_bf16 v[80:95], v[242:245], v[118:121], v[80:95]
	v_add_f32_e32 v162, v154, v162
	v_add_f32_e32 v162, v155, v162
	v_add_f32_e32 v162, v156, v162
	v_add_f32_e32 v162, v157, v162
	s_waitcnt lgkmcnt(0)
	v_mfma_f32_32x32x16_bf16 v[64:79], v[246:249], v[118:121], v[64:79]
	ds_read_b128 v[242:245], v193 offset:49152
	ds_read_b128 v[246:249], v193 offset:57344
	v_add_f32_e32 v162, v158, v162
	v_add_f32_e32 v162, v159, v162
	v_add_f32_e32 v162, v160, v162
	v_add_f32_e32 v211, v161, v162
	s_waitcnt lgkmcnt(1)
	v_mfma_f32_32x32x16_bf16 v[80:95], v[242:245], v[114:117], v[80:95]
	v_mov_b32_e32 v212, v211
	v_cvt_pk_bf16_f32 v162, v223, v224
	s_nop 0
	v_permlane32_swap_b32_e32 v211, v212
	s_waitcnt lgkmcnt(0)
	v_mfma_f32_32x32x16_bf16 v[64:79], v[246:249], v[114:117], v[64:79]
	ds_read_b128 v[242:245], v207 offset:49152
	ds_read_b128 v[246:249], v207 offset:57344
	v_permlane32_swap_b32_e32 v162, v164
	v_cvt_pk_bf16_f32 v166, v215, v217
	v_cvt_pk_bf16_f32 v167, v219, v221
	v_cvt_pk_bf16_f32 v170, v146, v147
	s_waitcnt lgkmcnt(1)
	v_mfma_f32_32x32x16_bf16 v[80:95], v[242:245], v[110:113], v[80:95]
	v_cvt_pk_bf16_f32 v171, v148, v149
	v_cvt_pk_bf16_f32 v172, v150, v151
	v_cvt_pk_bf16_f32 v173, v152, v153
	v_cvt_pk_bf16_f32 v174, v154, v155
	s_waitcnt lgkmcnt(0)
	v_mfma_f32_32x32x16_bf16 v[64:79], v[246:249], v[110:113], v[64:79]
	ds_read_b128 v[242:245], v206 offset:49152
	ds_read_b128 v[246:249], v206 offset:57344
	v_cvt_pk_bf16_f32 v175, v156, v157
	v_cvt_pk_bf16_f32 v176, v158, v159
	v_cvt_pk_bf16_f32 v177, v160, v161
	s_waitcnt lgkmcnt(1)
	v_mfma_f32_32x32x16_bf16 v[80:95], v[242:245], v[106:109], v[80:95]
	v_permlane32_swap_b32_e32 v166, v168
	v_permlane32_swap_b32_e32 v167, v169
	v_permlane32_swap_b32_e32 v170, v172
	s_waitcnt lgkmcnt(0)
	v_mfma_f32_32x32x16_bf16 v[64:79], v[246:249], v[106:109], v[64:79]
	v_permlane32_swap_b32_e32 v171, v173
	v_permlane32_swap_b32_e32 v174, v176
	v_permlane32_swap_b32_e32 v175, v177
	v_add_co_u32_e32 v146, vcc, s69, v182
	s_mov_b32 s8, 0xffff0000
	s_nop 0
	v_addc_co_u32_e32 v147, vcc, -1, v183, vcc
	v_add_co_u32_e32 v150, vcc, s8, v182
	s_mov_b32 s8, 0xff6e8000
	s_nop 0
	v_addc_co_u32_e32 v151, vcc, -1, v183, vcc
	v_add_co_u32_e32 v154, vcc, s8, v182
	s_mov_b32 s8, 0xff6f0000
	s_nop 0
	v_addc_co_u32_e32 v155, vcc, -1, v183, vcc
	v_add_co_u32_e32 v158, vcc, s8, v182
	global_load_dwordx4 v[146:149], v[146:147], off
	s_nop 0
	global_load_dwordx4 v[150:153], v[150:151], off
	v_addc_co_u32_e32 v159, vcc, -1, v183, vcc
	global_load_dwordx4 v[154:157], v[154:155], off
	s_nop 0
	global_load_dwordx4 v[158:161], v[158:159], off
	ds_read_b64_tr_b16 v[214:215], v179 offset:0
	ds_read_b64_tr_b16 v[216:217], v179 offset:0x800
	ds_read_b64_tr_b16 v[218:219], v179 offset:0x1000
	ds_read_b64_tr_b16 v[220:221], v179 offset:0x1800
	ds_read_b64_tr_b16 v[222:223], v179 offset:0x2000
	ds_read_b64_tr_b16 v[224:225], v179 offset:0x2800
	ds_read_b64_tr_b16 v[226:227], v179 offset:0x3000
	ds_read_b64_tr_b16 v[228:229], v179 offset:0x3800
	s_waitcnt vmcnt(4)
; #define SBAR() __builtin_amdgcn_sched_barrier(0)
; __device__ __forceinline__ void partialSM(f32x16& p0, f32x16& p1, float& m_reg, float& mn, float& alpha) {
;   constexpr float C = SCALE * 1.4426950408889634f;
;   float pmax = p0[0]; for (int r = 1; r < 16; ++r) pmax = fmaxf(pmax, p0[r]); for (int r = 0; r < 16; ++r) pmax = fmaxf(pmax, p1[r]);
;   { auto rr = __builtin_amdgcn_permlane32_swap(__float_as_uint(pmax), __float_as_uint(pmax), false, false);
;     pmax = fmaxf(__uint_as_float(rr[0]), __uint_as_float(rr[1])); }
;   if (__builtin_expect(__all(pmax - m_reg <= THR / SCALE), 1)) { mn = m_reg; alpha = 1.f; }
;   else { mn = fmaxf(m_reg, pmax); alpha = __builtin_amdgcn_exp2f((m_reg - mn) * C); m_reg = mn; }
;   float mnC = -mn * C;
;   for (int r = 0; r < 16; ++r) p0[r] = fmaf(p0[r], C, mnC); for (int r = 0; r < 16; ++r) p1[r] = fmaf(p1[r], C, mnC);
;   for (int r = 0; r < 16; ++r) p0[r] = __builtin_amdgcn_exp2f(p0[r]);
; template <int D0> __device__ __forceinline__ void pv_one(f32x16& od, int vb, bf16x8 pa0, bf16x8 pa1, bf16x8 pa2, bf16x8 pa3) {
;   const s16x4 l0 = tr_read<v_rd_off(D0, 0, 0)>(vb), h0 = tr_read<v_rd_off(D0, 0, 1)>(vb), l1 = tr_read<v_rd_off(D0, 1, 0)>(vb), h1 = tr_read<v_rd_off(D0, 1, 1)>(vb);
;   const s16x4 l2 = tr_read<v_rd_off(D0, 2, 0)>(vb), h2 = tr_read<v_rd_off(D0, 2, 1)>(vb), l3 = tr_read<v_rd_off(D0, 3, 0)>(vb), h3 = tr_read<v_rd_off(D0, 3, 1)>(vb);
;   asm volatile("s_waitcnt lgkmcnt(0)" ::: "memory"); SBAR();
;     ...
;   od = __builtin_amdgcn_mfma_f32_32x32x16_bf16(pa0, PK(l0, h0), od, 0, 0, 0);
;   od = __builtin_amdgcn_mfma_f32_32x32x16_bf16(pa1, PK(l1, h1), od, 0, 0, 0);
;   od = __builtin_amdgcn_mfma_f32_32x32x16_bf16(pa2, PK(l2, h2), od, 0, 0, 0);
;   od = __builtin_amdgcn_mfma_f32_32x32x16_bf16(pa3, PK(l3, h3), od, 0, 0, 0);
;     ...
; }
; __device__ __forceinline__ void pv_d0(f32x16* o, int vb, bf16x8 pa0, bf16x8 pa1, bf16x8 pa2, bf16x8 pa3) {
;   pv_one<0>(o[0], vb, pa0, pa1, pa2, pa3); pv_one<1>(o[1], vb, pa0, pa1, pa2, pa3); pv_one<2>(o[2], vb, pa0, pa1, pa2, pa3); pv_one<3>(o[3], vb, pa0, pa1, pa2, pa3);
	ds_write_b128 v202, v[102:105] offset:32768
	ds_write_b128 v203, v[142:145] offset:32768
	v_max_f32_e32 v232, v81, v81
	v_max_f32_e32 v233, v80, v80
	v_max_f32_e32 v232, v233, v232
	v_max3_f32 v232, v232, v82, v83
	v_max3_f32 v232, v232, v84, v85
	v_max3_f32 v232, v232, v86, v87
	v_max3_f32 v232, v232, v88, v89
	v_max3_f32 v232, v232, v90, v91
	v_max3_f32 v232, v232, v92, v93
	v_max3_f32 v232, v232, v94, v95
	v_max3_f32 v232, v232, v64, v65
	v_max3_f32 v232, v232, v66, v67
	s_waitcnt lgkmcnt(2)
	s_nop 0
	v_mfma_f32_32x32x16_bf16 v[0:15], v[162:165], v[214:217], v[0:15]
	ds_read_b64_tr_b16 v[214:215], v179 offset:0x200
	ds_read_b64_tr_b16 v[216:217], v179 offset:0xa00
	v_max3_f32 v232, v232, v68, v69
	v_max3_f32 v232, v232, v70, v71
	v_max3_f32 v232, v232, v72, v73
	v_max3_f32 v232, v232, v74, v75
	v_max3_f32 v232, v232, v76, v77
	v_max3_f32 v232, v232, v78, v79
	v_mfma_f32_32x32x16_bf16 v[0:15], v[166:169], v[218:221], v[0:15]
	ds_read_b64_tr_b16 v[218:219], v179 offset:0x1200
	ds_read_b64_tr_b16 v[220:221], v179 offset:0x1a00
	v_mov_b32_e32 v233, v232
	s_nop 1
	v_permlane32_swap_b32_e32 v232, v233
	v_max_f32_e32 v233, v233, v233
	v_max_f32_e32 v232, v232, v232
	v_max_f32_e32 v232, v232, v233
	v_mfma_f32_32x32x16_bf16 v[0:15], v[170:173], v[222:225], v[0:15]
	ds_read_b64_tr_b16 v[222:223], v179 offset:0x2200
	ds_read_b64_tr_b16 v[224:225], v179 offset:0x2a00
	v_sub_f32_e32 v233, v232, v210
	v_cmp_ge_f32_e32 vcc, s68, v233
	v_max_f32_e32 v233, v210, v210
	v_max_f32_e32 v232, v233, v232
	v_sub_f32_e32 v233, v210, v232
	v_mul_f32_e32 v233, 0x3e0293ee, v233
	v_mfma_f32_32x32x16_bf16 v[0:15], v[174:177], v[226:229], v[0:15]
	ds_read_b64_tr_b16 v[226:227], v179 offset:0x3200
	ds_read_b64_tr_b16 v[228:229], v179 offset:0x3a00
	s_cmp_eq_u64 vcc, exec
	s_cselect_b64 s[8:9], -1, 0
	v_exp_f32_e32 v233, v233
	s_waitcnt lgkmcnt(0)
	v_mfma_f32_32x32x16_bf16 v[48:63], v[162:165], v[214:217], v[48:63]
	ds_read_b64_tr_b16 v[214:215], v179 offset:0x400
	ds_read_b64_tr_b16 v[216:217], v179 offset:0xc00
	v_cndmask_b32_e64 v210, v232, v210, s[8:9]
	v_mul_f32_e32 v213, 0xbe0293ee, v210
	v_fmamk_f32 v80, v80, 0x3e0293ee, v213
	v_fmamk_f32 v81, v81, 0x3e0293ee, v213
	v_fmamk_f32 v82, v82, 0x3e0293ee, v213
	v_fmamk_f32 v83, v83, 0x3e0293ee, v213
	v_mfma_f32_32x32x16_bf16 v[48:63], v[166:169], v[218:221], v[48:63]
	ds_read_b64_tr_b16 v[218:219], v179 offset:0x1400
	ds_read_b64_tr_b16 v[220:221], v179 offset:0x1c00
	v_fmamk_f32 v84, v84, 0x3e0293ee, v213
	v_fmamk_f32 v85, v85, 0x3e0293ee, v213
	v_fmamk_f32 v86, v86, 0x3e0293ee, v213
	v_fmamk_f32 v87, v87, 0x3e0293ee, v213
	v_fmamk_f32 v88, v88, 0x3e0293ee, v213
	v_fmamk_f32 v89, v89, 0x3e0293ee, v213
	v_mfma_f32_32x32x16_bf16 v[48:63], v[170:173], v[222:225], v[48:63]
	ds_read_b64_tr_b16 v[222:223], v179 offset:0x2400
	ds_read_b64_tr_b16 v[224:225], v179 offset:0x2c00
	v_fmamk_f32 v90, v90, 0x3e0293ee, v213
	v_fmamk_f32 v91, v91, 0x3e0293ee, v213
	v_fmamk_f32 v92, v92, 0x3e0293ee, v213
	v_fmamk_f32 v93, v93, 0x3e0293ee, v213
	v_fmamk_f32 v94, v94, 0x3e0293ee, v213
	v_fmamk_f32 v95, v95, 0x3e0293ee, v213
	v_mfma_f32_32x32x16_bf16 v[48:63], v[174:177], v[226:229], v[48:63]
	ds_read_b64_tr_b16 v[226:227], v179 offset:0x3400
	ds_read_b64_tr_b16 v[228:229], v179 offset:0x3c00
	v_exp_f32_e32 v80, v80
	v_exp_f32_e32 v81, v81
	v_exp_f32_e32 v82, v82
	s_waitcnt lgkmcnt(0)
	v_mfma_f32_32x32x16_bf16 v[32:47], v[162:165], v[214:217], v[32:47]
	ds_read_b64_tr_b16 v[214:215], v179 offset:0x600
	ds_read_b64_tr_b16 v[216:217], v179 offset:0xe00
	v_exp_f32_e32 v83, v83
	v_exp_f32_e32 v84, v84
	v_exp_f32_e32 v85, v85
	v_mfma_f32_32x32x16_bf16 v[32:47], v[166:169], v[218:221], v[32:47]
	ds_read_b64_tr_b16 v[218:219], v179 offset:0x1600
	ds_read_b64_tr_b16 v[220:221], v179 offset:0x1e00
	v_exp_f32_e32 v86, v86
	v_exp_f32_e32 v87, v87
	v_exp_f32_e32 v88, v88
	v_mfma_f32_32x32x16_bf16 v[32:47], v[170:173], v[222:225], v[32:47]
	ds_read_b64_tr_b16 v[222:223], v179 offset:0x2600
	ds_read_b64_tr_b16 v[224:225], v179 offset:0x2e00
	v_exp_f32_e32 v89, v89
	v_exp_f32_e32 v90, v90
	v_exp_f32_e32 v91, v91
	v_mfma_f32_32x32x16_bf16 v[32:47], v[174:177], v[226:229], v[32:47]
	ds_read_b64_tr_b16 v[226:227], v179 offset:0x3600
	ds_read_b64_tr_b16 v[228:229], v179 offset:0x3e00
	v_exp_f32_e32 v92, v92
	v_exp_f32_e32 v93, v93
	s_waitcnt lgkmcnt(0)
	v_mfma_f32_32x32x16_bf16 v[16:31], v[162:165], v[214:217], v[16:31]
	v_exp_f32_e32 v94, v94
	v_exp_f32_e32 v95, v95
	v_mfma_f32_32x32x16_bf16 v[16:31], v[166:169], v[218:221], v[16:31]
	v_mfma_f32_32x32x16_bf16 v[16:31], v[170:173], v[222:225], v[16:31]
	v_mfma_f32_32x32x16_bf16 v[16:31], v[174:177], v[226:229], v[16:31]
	s_barrier
	s_waitcnt vmcnt(4)
	v_cndmask_b32_e64 v214, v233, 1.0, s[8:9]
	v_cmp_gt_f32_e32 vcc, 1.0, v214
	s_waitcnt vmcnt(7)
	ds_write_b128 v204, v[98:101]
	s_waitcnt vmcnt(6)
	ds_write_b128 v205, v[138:141]
	s_cbranch_vccz .LBB0_606
	s_and_saveexec_b64 s[12:13], s[6:7]
	ds_write_b32 v189, v214 offset:128
	s_or_b64 exec, exec, s[12:13]
	s_waitcnt lgkmcnt(0)
	v_add_u32_e32 v163, v181, v180
	ds_read_b128 v[164:167], v163 offset:224
	ds_read_b128 v[168:171], v163 offset:192
	ds_read_b128 v[172:175], v163 offset:160
	ds_read_b128 v[216:219], v163 offset:128
	s_waitcnt lgkmcnt(3)
	v_pk_mul_f32 v[12:13], v[12:13], v[164:165]
	s_waitcnt lgkmcnt(2)
	v_pk_mul_f32 v[8:9], v[8:9], v[168:169]
	s_waitcnt lgkmcnt(1)
	v_pk_mul_f32 v[4:5], v[4:5], v[172:173]
	v_pk_mul_f32 v[14:15], v[14:15], v[166:167]
	v_pk_mul_f32 v[10:11], v[10:11], v[170:171]
	v_pk_mul_f32 v[6:7], v[6:7], v[174:175]
	s_waitcnt lgkmcnt(0)
	v_pk_mul_f32 v[2:3], v[2:3], v[218:219]
	v_pk_mul_f32 v[0:1], v[0:1], v[216:217]
	v_pk_mul_f32 v[60:61], v[60:61], v[164:165]
	v_pk_mul_f32 v[56:57], v[56:57], v[168:169]
	v_pk_mul_f32 v[52:53], v[52:53], v[172:173]
	v_pk_mul_f32 v[62:63], v[62:63], v[166:167]
	v_pk_mul_f32 v[58:59], v[58:59], v[170:171]
	v_pk_mul_f32 v[54:55], v[54:55], v[174:175]
	v_pk_mul_f32 v[50:51], v[50:51], v[218:219]
	v_pk_mul_f32 v[48:49], v[48:49], v[216:217]
	v_pk_mul_f32 v[44:45], v[44:45], v[164:165]
	v_pk_mul_f32 v[40:41], v[40:41], v[168:169]
	v_pk_mul_f32 v[36:37], v[36:37], v[172:173]
	v_pk_mul_f32 v[46:47], v[46:47], v[166:167]
	v_pk_mul_f32 v[42:43], v[42:43], v[170:171]
	v_pk_mul_f32 v[38:39], v[38:39], v[174:175]
	v_pk_mul_f32 v[34:35], v[34:35], v[218:219]
	v_pk_mul_f32 v[32:33], v[32:33], v[216:217]
	v_pk_mul_f32 v[28:29], v[28:29], v[164:165]
	v_pk_mul_f32 v[24:25], v[24:25], v[168:169]
	v_pk_mul_f32 v[20:21], v[20:21], v[172:173]
	v_pk_mul_f32 v[30:31], v[30:31], v[166:167]
	v_pk_mul_f32 v[26:27], v[26:27], v[170:171]
	v_pk_mul_f32 v[22:23], v[22:23], v[174:175]
	v_pk_mul_f32 v[18:19], v[18:19], v[218:219]
	v_pk_mul_f32 v[16:17], v[16:17], v[216:217]

; #define SBAR() __builtin_amdgcn_sched_barrier(0)
; __device__ __forceinline__ void partialSM(f32x16& p0, f32x16& p1, float& m_reg, float& mn, float& alpha) {
;   constexpr float C = SCALE * 1.4426950408889634f;
;   float pmax = p0[0]; for (int r = 1; r < 16; ++r) pmax = fmaxf(pmax, p0[r]); for (int r = 0; r < 16; ++r) pmax = fmaxf(pmax, p1[r]);
;   { auto rr = __builtin_amdgcn_permlane32_swap(__float_as_uint(pmax), __float_as_uint(pmax), false, false);
;     pmax = fmaxf(__uint_as_float(rr[0]), __uint_as_float(rr[1])); }
;   if (__builtin_expect(__all(pmax - m_reg <= THR / SCALE), 1)) { mn = m_reg; alpha = 1.f; }
;   else { mn = fmaxf(m_reg, pmax); alpha = __builtin_amdgcn_exp2f((m_reg - mn) * C); m_reg = mn; }
;   float mnC = -mn * C;
;   for (int r = 0; r < 16; ++r) p0[r] = fmaf(p0[r], C, mnC); for (int r = 0; r < 16; ++r) p1[r] = fmaf(p1[r], C, mnC);
;   for (int r = 0; r < 16; ++r) p0[r] = __builtin_amdgcn_exp2f(p0[r]);
; template <int D0> __device__ __forceinline__ void pv_one(f32x16& od, int vb, bf16x8 pa0, bf16x8 pa1, bf16x8 pa2, bf16x8 pa3) {
;   const s16x4 l0 = tr_read<v_rd_off(D0, 0, 0)>(vb), h0 = tr_read<v_rd_off(D0, 0, 1)>(vb), l1 = tr_read<v_rd_off(D0, 1, 0)>(vb), h1 = tr_read<v_rd_off(D0, 1, 1)>(vb);
;   const s16x4 l2 = tr_read<v_rd_off(D0, 2, 0)>(vb), h2 = tr_read<v_rd_off(D0, 2, 1)>(vb), l3 = tr_read<v_rd_off(D0, 3, 0)>(vb), h3 = tr_read<v_rd_off(D0, 3, 1)>(vb);
;   asm volatile("s_waitcnt lgkmcnt(0)" ::: "memory"); SBAR();
;     ...
;   od = __builtin_amdgcn_mfma_f32_32x32x16_bf16(pa0, PK(l0, h0), od, 0, 0, 0);
;   od = __builtin_amdgcn_mfma_f32_32x32x16_bf16(pa1, PK(l1, h1), od, 0, 0, 0);
;   od = __builtin_amdgcn_mfma_f32_32x32x16_bf16(pa2, PK(l2, h2), od, 0, 0, 0);
;   od = __builtin_amdgcn_mfma_f32_32x32x16_bf16(pa3, PK(l3, h3), od, 0, 0, 0);
;     ...
; }
; __device__ __forceinline__ void pv_d0(f32x16* o, int vb, bf16x8 pa0, bf16x8 pa1, bf16x8 pa2, bf16x8 pa3) {
;   pv_one<0>(o[0], vb, pa0, pa1, pa2, pa3); pv_one<1>(o[1], vb, pa0, pa1, pa2, pa3); pv_one<2>(o[2], vb, pa0, pa1, pa2, pa3); pv_one<3>(o[3], vb, pa0, pa1, pa2, pa3);
.Lk_wd:
	ds_write_b128 v202, v[154:157] offset:49152
	ds_write_b128 v203, v[158:161] offset:49152
	v_max_f32_e32 v232, v81, v81
	v_max_f32_e32 v233, v80, v80
	v_max_f32_e32 v232, v233, v232
	v_max3_f32 v232, v232, v82, v83
	v_max3_f32 v232, v232, v84, v85
	v_max3_f32 v232, v232, v86, v87
	v_max3_f32 v232, v232, v88, v89
	v_max3_f32 v232, v232, v90, v91
	v_max3_f32 v232, v232, v92, v93
	v_max3_f32 v232, v232, v94, v95
	v_max3_f32 v232, v232, v64, v65
	v_max3_f32 v232, v232, v66, v67
	s_waitcnt lgkmcnt(2)
	s_nop 0
	v_mfma_f32_32x32x16_bf16 v[0:15], v[162:165], v[216:219], v[0:15]
	ds_read_b64_tr_b16 v[216:217], v191 offset:0x200
	ds_read_b64_tr_b16 v[218:219], v191 offset:0xa00
	v_max3_f32 v232, v232, v68, v69
	v_max3_f32 v232, v232, v70, v71
	v_max3_f32 v232, v232, v72, v73
	v_max3_f32 v232, v232, v74, v75
	v_max3_f32 v232, v232, v76, v77
	v_max3_f32 v232, v232, v78, v79
	v_mfma_f32_32x32x16_bf16 v[0:15], v[166:169], v[220:223], v[0:15]
	ds_read_b64_tr_b16 v[220:221], v191 offset:0x1200
	ds_read_b64_tr_b16 v[222:223], v191 offset:0x1a00
	v_mov_b32_e32 v233, v232
	s_nop 1
	v_permlane32_swap_b32_e32 v232, v233
	v_max_f32_e32 v233, v233, v233
	v_max_f32_e32 v232, v232, v232
	v_max_f32_e32 v232, v232, v233
	v_mfma_f32_32x32x16_bf16 v[0:15], v[170:173], v[224:227], v[0:15]
	ds_read_b64_tr_b16 v[224:225], v191 offset:0x2200
	ds_read_b64_tr_b16 v[226:227], v191 offset:0x2a00
	v_sub_f32_e32 v233, v232, v210
	v_cmp_ge_f32_e32 vcc, s68, v233
	v_max_f32_e32 v233, v210, v210
	v_max_f32_e32 v232, v233, v232
	v_sub_f32_e32 v233, v210, v232
	v_mul_f32_e32 v233, 0x3e0293ee, v233
	v_mfma_f32_32x32x16_bf16 v[0:15], v[174:177], v[242:245], v[0:15]
	ds_read_b64_tr_b16 v[242:243], v191 offset:0x3200
	ds_read_b64_tr_b16 v[244:245], v191 offset:0x3a00
	s_cmp_eq_u64 vcc, exec
	s_cselect_b64 s[8:9], -1, 0
	v_exp_f32_e32 v233, v233
	s_waitcnt lgkmcnt(0)
	v_mfma_f32_32x32x16_bf16 v[48:63], v[162:165], v[216:219], v[48:63]
	ds_read_b64_tr_b16 v[216:217], v191 offset:0x400
	ds_read_b64_tr_b16 v[218:219], v191 offset:0xc00
	v_cndmask_b32_e64 v210, v232, v210, s[8:9]
	v_mul_f32_e32 v250, 0xbe0293ee, v210
	v_fmamk_f32 v80, v80, 0x3e0293ee, v250
	v_fmamk_f32 v81, v81, 0x3e0293ee, v250
	v_fmamk_f32 v82, v82, 0x3e0293ee, v250
	v_fmamk_f32 v83, v83, 0x3e0293ee, v250
	v_mfma_f32_32x32x16_bf16 v[48:63], v[166:169], v[220:223], v[48:63]
	ds_read_b64_tr_b16 v[220:221], v191 offset:0x1400
	ds_read_b64_tr_b16 v[222:223], v191 offset:0x1c00
	v_fmamk_f32 v84, v84, 0x3e0293ee, v250
	v_fmamk_f32 v85, v85, 0x3e0293ee, v250
	v_fmamk_f32 v86, v86, 0x3e0293ee, v250
	v_fmamk_f32 v87, v87, 0x3e0293ee, v250
	v_fmamk_f32 v88, v88, 0x3e0293ee, v250
	v_fmamk_f32 v89, v89, 0x3e0293ee, v250
	v_mfma_f32_32x32x16_bf16 v[48:63], v[170:173], v[224:227], v[48:63]
	ds_read_b64_tr_b16 v[224:225], v191 offset:0x2400
	ds_read_b64_tr_b16 v[226:227], v191 offset:0x2c00
	v_fmamk_f32 v90, v90, 0x3e0293ee, v250
	v_fmamk_f32 v91, v91, 0x3e0293ee, v250
	v_fmamk_f32 v92, v92, 0x3e0293ee, v250
	v_fmamk_f32 v93, v93, 0x3e0293ee, v250
	v_fmamk_f32 v94, v94, 0x3e0293ee, v250
	v_fmamk_f32 v95, v95, 0x3e0293ee, v250
	v_mfma_f32_32x32x16_bf16 v[48:63], v[174:177], v[242:245], v[48:63]
	ds_read_b64_tr_b16 v[242:243], v191 offset:0x3400
	ds_read_b64_tr_b16 v[244:245], v191 offset:0x3c00
	v_exp_f32_e32 v80, v80
	v_exp_f32_e32 v81, v81
	v_exp_f32_e32 v82, v82
	s_waitcnt lgkmcnt(0)
	v_mfma_f32_32x32x16_bf16 v[32:47], v[162:165], v[216:219], v[32:47]
	ds_read_b64_tr_b16 v[216:217], v191 offset:0x600
	ds_read_b64_tr_b16 v[218:219], v191 offset:0xe00
	v_exp_f32_e32 v83, v83
	v_exp_f32_e32 v84, v84
	v_exp_f32_e32 v85, v85
	v_mfma_f32_32x32x16_bf16 v[32:47], v[166:169], v[220:223], v[32:47]
	ds_read_b64_tr_b16 v[220:221], v191 offset:0x1600
	ds_read_b64_tr_b16 v[222:223], v191 offset:0x1e00
	v_exp_f32_e32 v86, v86
	v_exp_f32_e32 v87, v87
	v_exp_f32_e32 v88, v88
	v_mfma_f32_32x32x16_bf16 v[32:47], v[170:173], v[224:227], v[32:47]
	ds_read_b64_tr_b16 v[224:225], v191 offset:0x2600
	ds_read_b64_tr_b16 v[226:227], v191 offset:0x2e00
	v_exp_f32_e32 v89, v89
	v_exp_f32_e32 v90, v90
	v_exp_f32_e32 v91, v91
	v_mfma_f32_32x32x16_bf16 v[32:47], v[174:177], v[242:245], v[32:47]
	ds_read_b64_tr_b16 v[242:243], v191 offset:0x3600
	ds_read_b64_tr_b16 v[244:245], v191 offset:0x3e00
	v_exp_f32_e32 v92, v92
	v_exp_f32_e32 v93, v93
	s_waitcnt lgkmcnt(0)
	v_mfma_f32_32x32x16_bf16 v[16:31], v[162:165], v[216:219], v[16:31]
	v_exp_f32_e32 v94, v94
	v_exp_f32_e32 v95, v95
	v_mfma_f32_32x32x16_bf16 v[16:31], v[166:169], v[220:223], v[16:31]
	v_mfma_f32_32x32x16_bf16 v[16:31], v[170:173], v[224:227], v[16:31]
	v_mfma_f32_32x32x16_bf16 v[16:31], v[174:177], v[242:245], v[16:31]
	s_barrier
	s_waitcnt vmcnt(4)
	v_cndmask_b32_e64 v213, v233, 1.0, s[8:9]
	v_cmp_gt_f32_e32 vcc, 1.0, v213
	ds_write_b128 v204, v[146:149] offset:16384
	ds_write_b128 v205, v[150:153] offset:16384
	s_cbranch_vccz .LBB0_612
	s_and_saveexec_b64 s[18:19], s[6:7]
	ds_write_b32 v189, v213 offset:128
	s_or_b64 exec, exec, s[18:19]
	s_waitcnt lgkmcnt(0)
	v_add_u32_e32 v158, v181, v180
	ds_read_b128 v[146:149], v158 offset:224
	ds_read_b128 v[150:153], v158 offset:192
	ds_read_b128 v[154:157], v158 offset:160
	ds_read_b128 v[158:161], v158 offset:128
	s_waitcnt lgkmcnt(3)
	v_pk_mul_f32 v[12:13], v[12:13], v[146:147]
	s_waitcnt lgkmcnt(2)
	v_pk_mul_f32 v[8:9], v[8:9], v[150:151]
	s_waitcnt lgkmcnt(1)
	v_pk_mul_f32 v[4:5], v[4:5], v[154:155]
	v_pk_mul_f32 v[14:15], v[14:15], v[148:149]
	v_pk_mul_f32 v[10:11], v[10:11], v[152:153]
	v_pk_mul_f32 v[6:7], v[6:7], v[156:157]
	s_waitcnt lgkmcnt(0)
	v_pk_mul_f32 v[2:3], v[2:3], v[160:161]
	v_pk_mul_f32 v[0:1], v[0:1], v[158:159]
	v_pk_mul_f32 v[60:61], v[60:61], v[146:147]
	v_pk_mul_f32 v[56:57], v[56:57], v[150:151]
	v_pk_mul_f32 v[52:53], v[52:53], v[154:155]
	v_pk_mul_f32 v[62:63], v[62:63], v[148:149]
	v_pk_mul_f32 v[58:59], v[58:59], v[152:153]
	v_pk_mul_f32 v[54:55], v[54:55], v[156:157]
	v_pk_mul_f32 v[50:51], v[50:51], v[160:161]
	v_pk_mul_f32 v[48:49], v[48:49], v[158:159]
	v_pk_mul_f32 v[44:45], v[44:45], v[146:147]
	v_pk_mul_f32 v[40:41], v[40:41], v[150:151]
	v_pk_mul_f32 v[36:37], v[36:37], v[154:155]
	v_pk_mul_f32 v[46:47], v[46:47], v[148:149]
	v_pk_mul_f32 v[42:43], v[42:43], v[152:153]
	v_pk_mul_f32 v[38:39], v[38:39], v[156:157]
	v_pk_mul_f32 v[34:35], v[34:35], v[160:161]
	v_pk_mul_f32 v[32:33], v[32:33], v[158:159]
	v_pk_mul_f32 v[28:29], v[28:29], v[146:147]
	v_pk_mul_f32 v[24:25], v[24:25], v[150:151]
	v_pk_mul_f32 v[20:21], v[20:21], v[154:155]
	v_pk_mul_f32 v[30:31], v[30:31], v[148:149]
	v_pk_mul_f32 v[26:27], v[26:27], v[152:153]
	v_pk_mul_f32 v[22:23], v[22:23], v[156:157]
	v_pk_mul_f32 v[18:19], v[18:19], v[160:161]
	v_pk_mul_f32 v[16:17], v[16:17], v[158:159]
